# split-barrier version plus loop-invariant out-norm gains hoisted out of the chunk loop
# baseline (speedup 1.0000x reference)
; template <bool STATE_ONLY>
; __device__ __forceinline__ void mlstm_group(const Args& a, LAS unsigned char* lds, int bh, int grp, int tid, int wave, int lane) {
;     ...
;     const int l_qk = tid >> 3, pc_qk = tid & 7;
;     const int j_n = tid >> 3, seg_n = tid & 7;
;     const size_t rowbase = (size_t)b * SEQ;
;     const int lp = tid & 31, pcg = tid >> 5;
;     constexpr int PD = STATE_ONLY ? ML_GROUP : 2;
;     u32x4 rq[PD], rk[PD], rv[PD][2], ro[PD][2]; u32x2 rk2[PD][2];
;     ...
; #pragma unroll
;     for (int d = 0; d < PD; ++d) ML_LOAD(c0 + d, d);
;     LAS float* T_av = (LAS float*)(lds + ML_TB); LAS float* T_dcol = T_av + 512; LAS float* T_pmx = T_dcol + 512; LAS float* T_bc = T_pmx + 512; LAS float* T_sc = T_bc + 512;
;     {
;         const size_t r = rowbase + (size_t)(c0 + wave) * 64 + lane;
;         const float gi = GT[r * 8 + h], gf = GT[r * 8 + 4 + h];
;         const float ipre = 15.f * fast_tanh((gi + b_i) * (1.f / 15.f)), fpre = 15.f * fast_tanh((gf + b_f) * (1.f / 15.f));
;         float bc = -__logf(1.f + __expf(-fpre));
; #pragma unroll
;         for (int o = 1; o < 64; o <<= 1) { const float t = __shfl_up(bc, o); if (lane >= o) bc += t; }
;         const float bl = __shfl(bc, 63);
;         const float av = bl - bc + ipre;
;         float amax = av;
; #pragma unroll
;         for (int o = 1; o < 64; o <<= 1) amax = fmaxf(amax, __shfl_xor(amax, o));
;         const float dcol = ipre - bc;
;         float pmx = dcol;
; #pragma unroll
;         for (int o = 1; o < 64; o <<= 1) { const float t = __shfl_up(pmx, o); if (lane >= o) pmx = fmaxf(pmx, t); }
;         T_av[wave * 64 + lane] = av; T_dcol[wave * 64 + lane] = dcol; T_pmx[wave * 64 + lane] = pmx; T_bc[wave * 64 + lane] = bc;
;         if (lane == 0) { T_sc[wave] = bl; T_sc[8 + wave] = amax;
;             if constexpr (STATE_ONLY) { CHS[(bh * 32 + c0 + wave) * 2] = bl; CHS[(bh * 32 + c0 + wave) * 2 + 1] = amax; } }
;     }
;     __syncthreads();
; #pragma unroll PD
;     for (int ci = 0; ci < ML_GROUP; ++ci) {
;         const int c = c0 + ci, si = ci % PD;
;         LAS float* n_cur = s_n + (c & 1) * 64; LAS float* n_nxt = s_n + ((c + 1) & 1) * 64;
;         const float bl = T_sc[ci], amax = T_sc[8 + ci];
;         const float m_new = fmaxf(bl + m_prev, amax);
;         const float decay = __expf(bl + m_prev - m_new);
;         if constexpr (STATE_ONLY) bsum += bl;
.LBB0_1239:
	s_or_b64 exec, exec, s[2:3]
	v_readlane_b32 s7, v245, 10
	s_cmp_lt_u32 s7, 64
	s_cselect_b64 s[42:43], -1, 0
	v_mul_u32_u24_e32 v78, 0x48, v80
	s_lshl_b32 s6, s78, 3
	v_lshlrev_b32_e32 v78, 1, v78
	v_lshlrev_b32_e32 v77, 1, v77
	s_and_b32 s6, s6, 0x1ffffff0
	v_add3_u32 v124, 0, v78, v77
	v_or_b32_e32 v77, s6, v63
	v_mul_lo_u32 v78, v77, s15
	s_waitcnt lgkmcnt(4)
	v_lshlrev_b32_e32 v79, 4, v62
	v_lshlrev_b32_e32 v119, 2, v152
	s_add_i32 s5, 0, 0x1a700
	v_add3_u32 v125, 0, v78, v79
	v_lshlrev_b32_e32 v78, 2, v77
	v_or_b32_e32 v92, s14, v63
	s_add_i32 s2, 0, 0x1a400
	s_add_i32 s4, 0, 0x1a600
	v_add_u32_e32 v123, s5, v119
	v_add_u32_e32 v128, s5, v78
	s_add_i32 s5, 0, 0x12000
	v_mul_lo_u32 v92, v92, s15
	s_add_i32 s3, 0, 0x1a500
	v_add_u32_e32 v122, s4, v119
	v_add_u32_e32 v126, s2, v78
	v_add_u32_e32 v127, s4, v78
	v_lshlrev_b32_e32 v78, 2, v73
	s_movk_i32 s4, 0x210
	v_add3_u32 v130, 0, v92, v79
	v_mov_b32_e32 v92, s5
	v_mul_u32_u24_e32 v72, 0x90, v72
	v_add_u32_e32 v120, s2, v119
	v_add_u32_e32 v121, s3, v119
	v_add_u32_e32 v129, s3, v78
	v_cmp_eq_u32_e64 s[2:3], 0, v76
	v_mad_u32_u24 v104, v80, s4, v92
	v_lshlrev_b32_e32 v105, 6, v76
	v_mul_u32_u24_e32 v76, 0x240, v75
	v_lshlrev_b32_e32 v92, 2, v74
	v_add3_u32 v134, 0, v72, v79
	v_or_b32_e32 v72, 48, v73
	v_mul_lo_u32 v91, v77, s4
	s_movk_i32 s4, 0x240
	v_add3_u32 v131, 0, v76, v92
	v_cmp_gt_u32_e64 s[28:29], v72, v77
	v_or_b32_e32 v72, 49, v73
	s_and_b32 s48, s7, 64
	v_mad_u32_u24 v132, v75, s4, v131
	v_mul_u32_u24_e32 v75, 0x90, v63
	v_cmp_gt_u32_e64 s[30:31], v72, v77
	v_or_b32_e32 v72, 50, v73
	v_add3_u32 v133, 0, v75, v79
	v_or_b32_e32 v75, 2, v73
	v_cmp_gt_u32_e64 s[34:35], v72, v77
	v_or_b32_e32 v72, 51, v73
	v_or_b32_e32 v63, s48, v63
	v_cmp_gt_u32_e64 s[8:9], v75, v77
	v_or_b32_e32 v75, 3, v73
	v_cmp_gt_u32_e64 s[36:37], v72, v77
	v_mul_u32_u24_e32 v72, 0x48, v63
	v_lshl_add_u32 v90, v73, 1, 0
	v_cmp_gt_u32_e64 s[10:11], v75, v77
	v_or_b32_e32 v75, 16, v73
	v_lshlrev_b32_e32 v72, 1, v72
	v_cmp_gt_u32_e64 s[12:13], v75, v77
	v_or_b32_e32 v75, 17, v73
	v_add_u32_e32 v135, v90, v72
	v_add3_u32 v136, 0, v72, v79
	v_or_b32_e32 v72, 16, v63
	v_cmp_gt_u32_e64 s[14:15], v75, v77
	v_or_b32_e32 v75, 18, v73
	v_mul_u32_u24_e32 v72, 0x48, v72
	v_cmp_gt_u32_e64 s[16:17], v75, v77
	v_or_b32_e32 v75, 19, v73
	v_lshlrev_b32_e32 v72, 1, v72
	v_add_u32_e32 v91, s5, v91
	v_cmp_gt_u32_e64 s[18:19], v75, v77
	v_or_b32_e32 v75, 32, v73
	s_lshl_b32 s48, s48, 2
	v_add_u32_e32 v138, v90, v72
	v_add3_u32 v139, 0, v72, v79
	v_or_b32_e32 v72, 32, v63
	s_add_i32 s47, 0, 0x1a800
	v_cmp_gt_u32_e64 s[20:21], v75, v77
	v_or_b32_e32 v75, 33, v73
	v_add3_u32 v137, v91, v78, s48
	v_mul_u32_u24_e32 v72, 0x48, v72
	v_or_b32_e32 v63, 48, v63
	s_lshl_b32 s48, s40, 2
	v_cmp_gt_u32_e64 s[22:23], v75, v77
	v_or_b32_e32 v75, 34, v73
	v_lshlrev_b32_e32 v72, 1, v72
	v_mul_u32_u24_e32 v63, 0x48, v63
	s_add_u32 s48, s60, s48
	v_cmp_gt_u32_e64 s[4:5], v73, v77
	v_cmp_lt_u32_e64 s[6:7], v73, v77
	v_cmp_gt_u32_e64 s[24:25], v75, v77
	v_or_b32_e32 v75, 35, v73
	v_add_u32_e32 v140, v90, v72
	v_add3_u32 v141, 0, v72, v79
	v_lshlrev_b32_e32 v63, 1, v63
	s_addc_u32 s49, s61, 0
	v_lshlrev_b32_e32 v72, 2, v56
	v_mov_b32_e32 v73, v81
	v_lshlrev_b32_e32 v59, 2, v80
	v_add_u32_e32 v142, v90, v63
	v_lshl_add_u64 v[90:91], s[48:49], 0, v[72:73]
	v_lshlrev_b32_e32 v62, 5, v62
	s_add_i32 s48, 0, 0x1a980
	v_add_u32_e32 v118, s47, v59
	v_add_u32_e32 v144, s47, v62
	s_add_i32 s47, 0, 0x1a880
	v_add_u32_e32 v147, s48, v62
	s_lshl_b64 s[48:49], s[38:39], 22
	s_lshl_b32 s39, s1, 20
	v_add_u32_e32 v145, s47, v62
	s_add_i32 s47, 0, 0x1a900
	s_or_b32 s39, s48, s39
	v_add_u32_e32 v148, s47, v59
	v_lshl_or_b32 v59, v80, 11, s39
	s_lshl_b32 s39, s81, 6
	v_add_u32_e32 v146, s47, v62
	s_and_b32 s47, s39, 0x300
	s_mul_hi_i32 s39, s38, 0x1200000
	s_mul_i32 s38, s38, 0x1200000
	s_mul_i32 s1, s1, 0x480000
	s_add_u32 s38, s38, s1
	s_addc_u32 s39, s39, 0
	v_add3_u32 v143, 0, v63, v79
	s_movk_i32 s1, 0x4800
	v_mov_b64_e32 v[62:63], s[38:39]
	v_mad_u64_u32 v[72:73], s[38:39], v74, s1, v[62:63]
	v_cmp_gt_u32_e64 s[26:27], v75, v77
	v_or3_b32 v92, v59, s47, v58
	v_or_b32_e32 v76, s40, v72
	v_mov_b32_e32 v77, v73
	v_lshrrev_b32_e32 v59, 1, v153
	s_add_u32 s38, s33, s44
	v_lshl_add_u64 v[94:95], v[76:77], 0, v[60:61]
	v_or_b32_e32 v72, s47, v72
	v_and_b32_e32 v60, 0x1f0, v59
	v_mov_b32_e32 v61, v81
	s_addc_u32 s39, 0, s45
	v_lshl_add_u64 v[96:97], v[72:73], 0, v[60:61]
	v_lshl_add_u64 v[60:61], s[38:39], 0, v[80:81]
	v_lshlrev_b64 v[98:99], 11, v[60:61]
	v_mad_u64_u32 v[60:61], s[38:39], v80, s46, v[62:63]
	v_or3_b32 v100, v60, s47, v58
	v_or_b32_e32 v60, s40, v60
	v_mov_b32_e32 v93, s49
	v_or3_b32 v98, v98, s47, v58
	v_mov_b32_e32 v101, v61
	v_lshl_add_u64 v[102:103], v[60:61], 0, v[56:57]
	v_lshlrev_b32_e32 v149, 3, v74
	s_movk_i32 s1, 0xffe0
	s_mov_b32 s33, 0xffff0000
	s_mov_b64 s[44:45], 0x7920800
	v_mov_b32_e32 v150, 0x358637bd
	s_mov_b32 s40, 0x19800000
	s_mov_b64 s[46:47], 0x79b0800
	s_mov_b32 s58, 0x19820000
	s_mov_b64 s[48:49], 0x40000
	s_mov_b64 s[50:51], 0x120000
	v_add_u32_e32 v151, v104, v105
	s_waitcnt lgkmcnt(0)
	s_barrier
	global_load_dwordx2 v[202:203], v[90:91], off
	global_load_dwordx2 v[204:205], v[90:91], off offset:8
	global_load_dwordx2 v[206:207], v[90:91], off offset:16
	global_load_dwordx2 v[208:209], v[90:91], off offset:24
	global_load_dwordx2 v[210:211], v[90:91], off offset:32
	global_load_dwordx2 v[212:213], v[90:91], off offset:40
	global_load_dwordx2 v[214:215], v[90:91], off offset:48
	global_load_dwordx2 v[216:217], v[90:91], off offset:56
	s_branch .LBB0_1241
; #define LAS __attribute__((address_space(3)))
; __device__ __forceinline__ unsigned cvt_pk_bf16(float lo, float hi) { unsigned r; asm volatile("v_cvt_pk_bf16_f32 %0, %1, %2" : "=v"(r) : "v"(lo), "v"(hi)); return r; }
; __device__ __forceinline__ bf16_t f2bf(float f) { return (bf16_t)(cvt_pk_bf16(f, 0.f) & 0xffffu); }
; __device__ __forceinline__ float bflo(unsigned w) { return __uint_as_float(w << 16); }
; __device__ __forceinline__ float bfhi(unsigned w) { return __uint_as_float(w & 0xffff0000u); }
; __device__ __forceinline__ float sigm(float x) { return __builtin_amdgcn_rcpf(1.f + __expf(-x)); }
; template <bool STATE_ONLY>
; __device__ __forceinline__ void mlstm_group(const Args& a, LAS unsigned char* lds, int bh, int grp, int tid, int wave, int lane) {
;     ...
;         if constexpr (!STATE_ONLY) {
; #pragma unroll
;             for (int kt = 0; kt < 4; ++kt)
; #pragma unroll
;                 for (int i = 0; i < 4; ++i) CB[(16 * wave + 4 * fq + i) * LP + 16 * kt + fr] = f2bf(cacc[kt][i]);
;             float hv[16]; float sq = 0.f;
; #pragma unroll
;             for (int q = 0; q < 4; ++q) { const f32x4 t = *(const LAS f32x4*)(HB + j_n * HBP + seg_n * 16 + 4 * q); hv[4 * q] = t[0]; hv[4 * q + 1] = t[1]; hv[4 * q + 2] = t[2]; hv[4 * q + 3] = t[3];
;                 sq += (t[0] * t[0] + t[1] * t[1]) + (t[2] * t[2] + t[3] * t[3]); }
;             sq += __shfl_xor(sq, 1); sq += __shfl_xor(sq, 2); sq += __shfl_xor(sq, 4);
;             const float rn = rsqrtf(sq * (1.0f / 128.f) + NORM_EPS);
;             const float* gp = a.gno + h * 128 + seg_n * 16;
;             float ov[16];
; #pragma unroll
;             for (int q = 0; q < 4; ++q) { ov[2 * q] = bflo(og0[q]); ov[2 * q + 1] = bfhi(og0[q]); ov[8 + 2 * q] = bflo(og1[q]); ov[8 + 2 * q + 1] = bfhi(og1[q]); }
;             unsigned pk[8];
; #pragma unroll
;             for (int q = 0; q < 8; ++q) { const float v0 = hv[2 * q] * rn * gp[2 * q] * sigm(ov[2 * q]), v1 = hv[2 * q + 1] * rn * gp[2 * q + 1] * sigm(ov[2 * q + 1]); pk[q] = cvt_pk_bf16(v0, v1); }
.LBB0_1240:
	s_or_b64 exec, exec, s[38:39]
	s_waitcnt lgkmcnt(0)
	s_barrier
	v_cvt_pk_bf16_f32 v72, v52, v81
	ds_write_b16 v112, v72 offset:55296
	v_cvt_pk_bf16_f32 v72, v53, v81
	ds_write_b16 v112, v72 offset:55440
	v_cvt_pk_bf16_f32 v72, v54, v81
	ds_write_b16 v112, v72 offset:55584
	v_cvt_pk_bf16_f32 v72, v55, v81
	ds_write_b16 v112, v72 offset:55728
	v_cvt_pk_bf16_f32 v72, v44, v81
	ds_write_b16 v112, v72 offset:55328
	v_cvt_pk_bf16_f32 v72, v45, v81
	ds_write_b16 v112, v72 offset:55472
	v_cvt_pk_bf16_f32 v72, v46, v81
	ds_write_b16 v112, v72 offset:55616
	v_cvt_pk_bf16_f32 v72, v47, v81
	ds_write_b16 v112, v72 offset:55760
	v_cvt_pk_bf16_f32 v72, v48, v81
	ds_write_b16 v112, v72 offset:55360
	v_cvt_pk_bf16_f32 v72, v49, v81
	ds_write_b16 v112, v72 offset:55504
	v_cvt_pk_bf16_f32 v72, v50, v81
	ds_write_b16 v112, v72 offset:55648
	v_cvt_pk_bf16_f32 v72, v51, v81
	ds_write_b16 v112, v72 offset:55792
	v_cvt_pk_bf16_f32 v72, v40, v81
	ds_write_b16 v112, v72 offset:55392
	v_cvt_pk_bf16_f32 v72, v41, v81
	ds_write_b16 v112, v72 offset:55536
	v_cvt_pk_bf16_f32 v72, v42, v81
	ds_write_b16 v112, v72 offset:55680
	v_cvt_pk_bf16_f32 v72, v43, v81
	ds_write_b16 v112, v72 offset:55824
	ds_read_b128 v[76:79], v151
	ds_read_b128 v[104:107], v151 offset:16
	ds_read_b128 v[108:111], v151 offset:32
	ds_read_b128 v[72:75], v151 offset:48
	s_add_i32 s41, s41, 2
	s_waitcnt lgkmcnt(3)
	v_pk_mul_f32 v[158:159], v[78:79], v[78:79]
	v_pk_mul_f32 v[160:161], v[76:77], v[76:77]
	s_add_i32 s1, s1, 8
	v_pk_mov_b32 v[162:163], v[160:161], v[158:159] op_sel:[1,0]
	v_mov_b32_e32 v161, v159
	v_pk_add_f32 v[158:159], v[162:163], v[160:161]
	s_waitcnt lgkmcnt(2)
	v_pk_mul_f32 v[160:161], v[106:107], v[106:107]
	v_pk_mul_f32 v[162:163], v[104:105], v[104:105]
	s_waitcnt lgkmcnt(0)
	v_mul_f32_e32 v80, v72, v72
	v_pk_mov_b32 v[164:165], v[162:163], v[160:161] op_sel:[1,0]
	v_mov_b32_e32 v163, v161
	v_pk_add_f32 v[160:161], v[164:165], v[162:163]
	v_mul_f32_e32 v155, v73, v73
	v_pk_add_f32 v[158:159], v[158:159], v[158:159] op_sel:[0,1] op_sel_hi:[1,0]
	v_pk_add_f32 v[160:161], v[160:161], v[160:161] op_sel:[0,1] op_sel_hi:[1,0]
	v_mov_b32_e32 v159, v80
	v_mov_b32_e32 v161, v155
	v_mul_f32_e32 v80, v109, v109
	v_mul_f32_e32 v162, v74, v74
	v_pk_add_f32 v[158:159], v[158:159], v[160:161]
	v_pk_fma_f32 v[160:161], v[108:109], v[108:109], v[80:81] op_sel_hi:[1,1,0]
	v_mul_f32_e32 v80, v111, v111
	v_mul_f32_e32 v164, v75, v75
	v_mov_b32_e32 v161, v162
	v_pk_fma_f32 v[162:163], v[110:111], v[110:111], v[80:81] op_sel_hi:[1,1,0]
	v_lshl_add_u64 v[94:95], v[94:95], 0, s[50:51]
	v_mov_b32_e32 v163, v164
	v_pk_add_f32 v[160:161], v[160:161], v[162:163]
	v_lshl_add_u64 v[96:97], v[96:97], 0, s[50:51]
	v_pk_add_f32 v[158:159], v[158:159], v[160:161]
	v_lshl_add_u64 v[98:99], v[98:99], 0, s[48:49]
	v_add_f32_e32 v80, v158, v159
	ds_bpermute_b32 v155, v113, v80
	v_lshlrev_b32_e32 v158, 16, v36
	v_mul_f32_e32 v158, 0xbfb8aa3b, v158
	v_and_b32_e32 v36, 0xffff0000, v36
	v_exp_f32_e32 v158, v158
	s_waitcnt lgkmcnt(0)
	v_add_f32_e32 v80, v80, v155
	ds_bpermute_b32 v155, v114, v80
	v_mul_f32_e32 v36, 0xbfb8aa3b, v36
	v_exp_f32_e32 v36, v36
	v_add_f32_e32 v158, 1.0, v158
	v_lshl_add_u64 v[100:101], v[100:101], 0, s[50:51]
	s_waitcnt lgkmcnt(0)
	v_add_f32_e32 v80, v80, v155
	ds_bpermute_b32 v155, v115, v80
	v_add_f32_e32 v36, 1.0, v36
	v_rcp_f32_e32 v36, v36
	v_lshl_add_u64 v[102:103], v[102:103], 0, s[50:51]
	v_add_u32_e32 v119, 0x200, v119
	s_waitcnt lgkmcnt(0)
	v_add_f32_e32 v80, v80, v155
	v_fmamk_f32 v80, v80, 0x3c000000, v150
	v_mul_f32_e32 v155, 0x4b800000, v80
	v_cmp_gt_f32_e32 vcc, s0, v80
	v_add_u32_e32 v149, 0x200, v149
	s_cmp_lg_u32 s1, 0
	v_cndmask_b32_e32 v80, v80, v155, vcc
	v_rsq_f32_e32 v80, v80
	v_rcp_f32_e32 v155, v158
	v_mul_f32_e32 v158, 0x45800000, v80
	v_cndmask_b32_e32 v80, v80, v158, vcc
	v_mul_f32_e32 v76, v76, v80
	v_mul_f32_e32 v77, v77, v80
	s_waitcnt vmcnt(0)
; __device__ __forceinline__ unsigned cvt_pk_bf16(float lo, float hi) { unsigned r; asm volatile("v_cvt_pk_bf16_f32 %0, %1, %2" : "=v"(r) : "v"(lo), "v"(hi)); return r; }
; __device__ __forceinline__ float bflo(unsigned w) { return __uint_as_float(w << 16); }
; __device__ __forceinline__ float bfhi(unsigned w) { return __uint_as_float(w & 0xffff0000u); }
; __device__ __forceinline__ float sigm(float x) { return __builtin_amdgcn_rcpf(1.f + __expf(-x)); }
; template <bool STATE_ONLY>
; __device__ __forceinline__ void mlstm_group(const Args& a, LAS unsigned char* lds, int bh, int grp, int tid, int wave, int lane) {
;     ...
;             const float* gp = a.gno + h * 128 + seg_n * 16;
;             float ov[16];
; #pragma unroll
;             for (int q = 0; q < 4; ++q) { ov[2 * q] = bflo(og0[q]); ov[2 * q + 1] = bfhi(og0[q]); ov[8 + 2 * q] = bflo(og1[q]); ov[8 + 2 * q + 1] = bfhi(og1[q]); }
;             unsigned pk[8];
; #pragma unroll
;             for (int q = 0; q < 8; ++q) { const float v0 = hv[2 * q] * rn * gp[2 * q] * sigm(ov[2 * q]), v1 = hv[2 * q + 1] * rn * gp[2 * q + 1] * sigm(ov[2 * q + 1]); pk[q] = cvt_pk_bf16(v0, v1); }
;             bf16_t* dst = HO + (rowbase + (size_t)c * 64 + j_n) * DM + h * 128 + seg_n * 16;
;             *(u32x4*)dst = (u32x4){pk[0], pk[1], pk[2], pk[3]}; *(u32x4*)(dst + 8) = (u32x4){pk[4], pk[5], pk[6], pk[7]};
	v_mov_b32_e32 v156, v202
	v_mov_b32_e32 v157, v203
	v_mul_f32_e32 v76, v156, v76
	v_mul_f32_e32 v77, v157, v77
	v_mul_f32_e32 v76, v155, v76
	v_mul_f32_e32 v36, v36, v77
	v_cvt_pk_bf16_f32 v76, v76, v36
	v_lshlrev_b32_e32 v36, 16, v37
	v_and_b32_e32 v37, 0xffff0000, v37
	v_mul_f32_e32 v36, 0xbfb8aa3b, v36
	v_mul_f32_e32 v37, 0xbfb8aa3b, v37
	v_exp_f32_e32 v36, v36
	v_exp_f32_e32 v37, v37
	v_mul_f32_e32 v77, v78, v80
	v_mul_f32_e32 v78, v79, v80
	v_add_f32_e32 v36, 1.0, v36
	v_add_f32_e32 v37, 1.0, v37
	v_rcp_f32_e32 v36, v36
	v_rcp_f32_e32 v37, v37
	v_mul_f32_e32 v79, v104, v80
	v_mul_f32_e32 v104, v105, v80
	v_mov_b32_e32 v156, v204
	v_mov_b32_e32 v157, v205
	v_mul_f32_e32 v77, v156, v77
	v_mul_f32_e32 v78, v157, v78
	v_mul_f32_e32 v36, v36, v77
	v_mul_f32_e32 v37, v37, v78
	v_cvt_pk_bf16_f32 v77, v36, v37
	v_lshlrev_b32_e32 v78, 16, v38
	v_and_b32_e32 v38, 0xffff0000, v38
	v_mul_f32_e32 v78, 0xbfb8aa3b, v78
	v_mul_f32_e32 v38, 0xbfb8aa3b, v38
	v_exp_f32_e32 v78, v78
	v_exp_f32_e32 v38, v38
	v_add_f32_e32 v78, 1.0, v78
	v_add_f32_e32 v38, 1.0, v38
	v_rcp_f32_e32 v78, v78
	v_rcp_f32_e32 v38, v38
	v_mov_b32_e32 v36, v206
	v_mov_b32_e32 v37, v207
	v_mul_f32_e32 v36, v36, v79
	v_mul_f32_e32 v37, v37, v104
	v_mul_f32_e32 v36, v78, v36
	v_mul_f32_e32 v37, v38, v37
	v_cvt_pk_bf16_f32 v78, v36, v37
	v_lshlrev_b32_e32 v38, 16, v39
	v_and_b32_e32 v39, 0xffff0000, v39
	v_mul_f32_e32 v38, 0xbfb8aa3b, v38
	v_mul_f32_e32 v39, 0xbfb8aa3b, v39
	v_exp_f32_e32 v38, v38
	v_exp_f32_e32 v39, v39
	v_mul_f32_e32 v79, v106, v80
	v_mul_f32_e32 v104, v107, v80
	v_add_f32_e32 v38, 1.0, v38
	v_add_f32_e32 v39, 1.0, v39
	v_rcp_f32_e32 v38, v38
	v_rcp_f32_e32 v39, v39
	v_lshlrev_b32_e32 v107, 16, v31
	v_mov_b32_e32 v36, v208
	v_mov_b32_e32 v37, v209
	v_mul_f32_e32 v36, v36, v79
	v_mul_f32_e32 v37, v37, v104
	v_mul_f32_e32 v36, v38, v36
	v_mul_f32_e32 v37, v39, v37
	v_cvt_pk_bf16_f32 v79, v36, v37
	v_lshlrev_b32_e32 v38, 16, v28
	v_and_b32_e32 v28, 0xffff0000, v28
	v_mul_f32_e32 v38, 0xbfb8aa3b, v38
	v_mul_f32_e32 v28, 0xbfb8aa3b, v28
	v_exp_f32_e32 v38, v38
	v_exp_f32_e32 v28, v28
	v_mul_f32_e32 v39, v108, v80
	v_mul_f32_e32 v104, v109, v80
	v_add_f32_e32 v38, 1.0, v38
	v_add_f32_e32 v28, 1.0, v28
	v_rcp_f32_e32 v38, v38
	v_rcp_f32_e32 v28, v28
	v_lshl_add_u64 v[108:109], s[74:75], 0, v[92:93]
	v_lshl_add_u64 v[92:93], v[92:93], 0, s[48:49]
	v_mov_b32_e32 v36, v210
	v_mov_b32_e32 v37, v211
	v_mul_f32_e32 v36, v36, v39
	v_mul_f32_e32 v37, v104, v37
	v_mul_f32_e32 v36, v38, v36
	v_mul_f32_e32 v28, v28, v37
	v_cvt_pk_bf16_f32 v104, v36, v28
	v_lshlrev_b32_e32 v28, 16, v29
	v_and_b32_e32 v29, 0xffff0000, v29
	v_mul_f32_e32 v28, 0xbfb8aa3b, v28
	v_mul_f32_e32 v29, 0xbfb8aa3b, v29
	v_exp_f32_e32 v28, v28
	v_exp_f32_e32 v29, v29
	v_mul_f32_e32 v38, v110, v80
	v_mul_f32_e32 v39, v111, v80
	v_add_f32_e32 v28, 1.0, v28
	v_add_f32_e32 v29, 1.0, v29
	v_rcp_f32_e32 v28, v28
	v_rcp_f32_e32 v29, v29
	v_and_b32_e32 v110, 0xffff0000, v31
	v_mov_b32_e32 v36, v212
	v_mov_b32_e32 v37, v213
	v_mul_f32_e32 v36, v38, v36
	v_mul_f32_e32 v37, v39, v37
	v_mul_f32_e32 v28, v28, v36
	v_mul_f32_e32 v29, v29, v37
	v_cvt_pk_bf16_f32 v105, v28, v29
	v_lshlrev_b32_e32 v36, 16, v30
	v_and_b32_e32 v30, 0xffff0000, v30
	v_mul_f32_e32 v36, 0xbfb8aa3b, v36
	v_mul_f32_e32 v30, 0xbfb8aa3b, v30
	v_exp_f32_e32 v36, v36
	v_exp_f32_e32 v30, v30
	v_mul_f32_e32 v37, v72, v80
	v_mul_f32_e32 v38, v73, v80
	v_add_f32_e32 v36, 1.0, v36
	v_add_f32_e32 v30, 1.0, v30
	v_rcp_f32_e32 v36, v36
	v_rcp_f32_e32 v30, v30
	v_mov_b32_e32 v28, v214
	v_mov_b32_e32 v29, v215
	v_mul_f32_e32 v28, v37, v28
	v_mul_f32_e32 v29, v38, v29
	v_mul_f32_e32 v28, v36, v28
	v_mul_f32_e32 v29, v30, v29
	v_cvt_pk_bf16_f32 v106, v28, v29
	v_mov_b64_e32 v[36:37], v[64:65]
	v_mov_b64_e32 v[38:39], v[66:67]
	v_mov_b64_e32 v[66:67], v[62:63]
	v_mov_b64_e32 v[64:65], v[60:61]
	v_mul_f32_e32 v60, 0xbfb8aa3b, v107
	v_mul_f32_e32 v61, 0xbfb8aa3b, v110
	v_exp_f32_e32 v62, v60
	v_exp_f32_e32 v63, v61
	v_mov_b64_e32 v[28:29], v[68:69]
	v_mov_b64_e32 v[30:31], v[70:71]
	v_add_f32_e32 v62, 1.0, v62
	v_add_f32_e32 v63, 1.0, v63
	v_rcp_f32_e32 v62, v62
	v_rcp_f32_e32 v63, v63
	v_mul_f32_e32 v68, v74, v80
	v_mul_f32_e32 v69, v75, v80
	v_add_co_u32_e32 v60, vcc, s58, v108
	v_mov_b32_e32 v72, v216
	v_mov_b32_e32 v73, v217
	v_mul_f32_e32 v68, v68, v72
	v_mul_f32_e32 v69, v69, v73
	v_mul_f32_e32 v62, v62, v68
	v_mul_f32_e32 v63, v63, v69
	v_mov_b64_e32 v[70:71], v[58:59]
	v_addc_co_u32_e32 v61, vcc, 0, v109, vcc
	v_mov_b64_e32 v[68:69], v[56:57]
	v_cvt_pk_bf16_f32 v107, v62, v63
	global_store_dwordx4 v[60:61], v[76:79], off
	global_store_dwordx4 v[60:61], v[104:107], off offset:16
	s_cbranch_scc0 .LBB0_1253

; #define LAS __attribute__((address_space(3)))
; __device__ __forceinline__ bf16_t f2bf(float f) { return (bf16_t)(cvt_pk_bf16(f, 0.f) & 0xffffu); }
; template <bool STATE_ONLY>
; __device__ __forceinline__ void mlstm_group(const Args& a, LAS unsigned char* lds, int bh, int grp, int tid, int wave, int lane) {
;     ...
;         if constexpr (!STATE_ONLY) {
; #pragma unroll
;             for (int kt = 0; kt < 4; ++kt)
; #pragma unroll
;                 for (int i = 0; i < 4; ++i) CB[(16 * wave + 4 * fq + i) * LP + 16 * kt + fr] = f2bf(cacc[kt][i]);
;             float hv[16]; float sq = 0.f;
; #pragma unroll
;             for (int q = 0; q < 4; ++q) { const f32x4 t = *(const LAS f32x4*)(HB + j_n * HBP + seg_n * 16 + 4 * q); hv[4 * q] = t[0]; hv[4 * q + 1] = t[1]; hv[4 * q + 2] = t[2]; hv[4 * q + 3] = t[3];
;                 sq += (t[0] * t[0] + t[1] * t[1]) + (t[2] * t[2] + t[3] * t[3]); }
;             sq += __shfl_xor(sq, 1); sq += __shfl_xor(sq, 2); sq += __shfl_xor(sq, 4);
;             const float rn = rsqrtf(sq * (1.0f / 128.f) + NORM_EPS);
.LBB0_1247:
	s_or_b64 exec, exec, s[56:57]
	s_waitcnt lgkmcnt(0)
	s_barrier
	v_cvt_pk_bf16_f32 v72, v52, v81
	ds_write_b16 v112, v72 offset:55296
	v_cvt_pk_bf16_f32 v72, v53, v81
	ds_write_b16 v112, v72 offset:55440
	v_cvt_pk_bf16_f32 v72, v54, v81
	ds_write_b16 v112, v72 offset:55584
	v_cvt_pk_bf16_f32 v72, v55, v81
	ds_write_b16 v112, v72 offset:55728
	v_cvt_pk_bf16_f32 v72, v44, v81
	ds_write_b16 v112, v72 offset:55328
	v_cvt_pk_bf16_f32 v72, v45, v81
	ds_write_b16 v112, v72 offset:55472
	v_cvt_pk_bf16_f32 v72, v46, v81
	ds_write_b16 v112, v72 offset:55616
	v_cvt_pk_bf16_f32 v72, v47, v81
	ds_write_b16 v112, v72 offset:55760
	v_cvt_pk_bf16_f32 v72, v48, v81
	ds_write_b16 v112, v72 offset:55360
	v_cvt_pk_bf16_f32 v72, v49, v81
	ds_write_b16 v112, v72 offset:55504
	v_cvt_pk_bf16_f32 v72, v50, v81
	ds_write_b16 v112, v72 offset:55648
	v_cvt_pk_bf16_f32 v72, v51, v81
	ds_write_b16 v112, v72 offset:55792
	v_cvt_pk_bf16_f32 v72, v40, v81
	ds_write_b16 v112, v72 offset:55392
	v_cvt_pk_bf16_f32 v72, v41, v81
	ds_write_b16 v112, v72 offset:55536
	v_cvt_pk_bf16_f32 v72, v42, v81
	ds_write_b16 v112, v72 offset:55680
	v_cvt_pk_bf16_f32 v72, v43, v81
	ds_write_b16 v112, v72 offset:55824
	ds_read_b128 v[76:79], v151
	ds_read_b128 v[162:165], v151 offset:16
	ds_read_b128 v[166:169], v151 offset:32
	ds_read_b128 v[72:75], v151 offset:48
	s_add_i32 s54, s59, 0x1ca24
	s_waitcnt lgkmcnt(3)
	v_pk_mul_f32 v[172:173], v[78:79], v[78:79]
	v_pk_mul_f32 v[174:175], v[76:77], v[76:77]
	s_add_i32 s55, s59, 0x1ca44
	v_pk_mov_b32 v[176:177], v[174:175], v[172:173] op_sel:[1,0]
	v_mov_b32_e32 v175, v173
	v_pk_add_f32 v[172:173], v[176:177], v[174:175]
	s_waitcnt lgkmcnt(2)
	v_pk_mul_f32 v[174:175], v[164:165], v[164:165]
	v_pk_mul_f32 v[176:177], v[162:163], v[162:163]
	s_waitcnt lgkmcnt(0)
	v_mul_f32_e32 v80, v72, v72
	v_pk_mov_b32 v[178:179], v[176:177], v[174:175] op_sel:[1,0]
	v_mov_b32_e32 v177, v175
	v_pk_add_f32 v[174:175], v[178:179], v[176:177]
	v_mul_f32_e32 v176, v73, v73
	v_pk_add_f32 v[172:173], v[172:173], v[172:173] op_sel:[0,1] op_sel_hi:[1,0]
	v_pk_add_f32 v[174:175], v[174:175], v[174:175] op_sel:[0,1] op_sel_hi:[1,0]
	v_mov_b32_e32 v173, v80
	v_mov_b32_e32 v175, v176
	v_mul_f32_e32 v80, v167, v167
	v_mul_f32_e32 v177, v74, v74
	v_pk_add_f32 v[172:173], v[172:173], v[174:175]
	v_pk_fma_f32 v[174:175], v[166:167], v[166:167], v[80:81] op_sel_hi:[1,1,0]
	v_mul_f32_e32 v80, v169, v169
	v_mul_f32_e32 v178, v75, v75
	v_mov_b32_e32 v175, v177
	v_pk_fma_f32 v[176:177], v[168:169], v[168:169], v[80:81] op_sel_hi:[1,1,0]
	s_nop 0
	v_mov_b32_e32 v177, v178
	v_pk_add_f32 v[174:175], v[174:175], v[176:177]
	s_nop 0
	v_pk_add_f32 v[172:173], v[172:173], v[174:175]
	s_nop 0
	v_add_f32_e32 v80, v172, v173
	ds_bpermute_b32 v172, v113, v80
	v_lshlrev_b32_e32 v173, 16, v68
	v_and_b32_e32 v68, 0xffff0000, v68
	v_mul_f32_e32 v173, 0xbfb8aa3b, v173
	v_mul_f32_e32 v68, 0xbfb8aa3b, v68
	s_waitcnt lgkmcnt(0)
	v_add_f32_e32 v80, v80, v172
	ds_bpermute_b32 v172, v114, v80
	v_exp_f32_e32 v173, v173
	v_exp_f32_e32 v68, v68
	s_waitcnt lgkmcnt(0)
	v_add_f32_e32 v80, v80, v172
	ds_bpermute_b32 v172, v115, v80
	v_add_f32_e32 v173, 1.0, v173
	v_add_f32_e32 v68, 1.0, v68
	v_rcp_f32_e32 v68, v68
	s_waitcnt lgkmcnt(0)
	v_add_f32_e32 v80, v80, v172
	v_fmamk_f32 v80, v80, 0x3c000000, v150
	v_mul_f32_e32 v172, 0x4b800000, v80
	v_cmp_gt_f32_e32 vcc, s0, v80
	s_nop 1
	v_cndmask_b32_e32 v80, v80, v172, vcc
	v_rsq_f32_e32 v80, v80
	v_rcp_f32_e32 v172, v173
	v_mul_f32_e32 v173, 0x45800000, v80
	v_cndmask_b32_e32 v80, v80, v173, vcc
	v_mul_f32_e32 v76, v76, v80
	v_mul_f32_e32 v77, v77, v80
	v_mul_f32_e32 v78, v78, v80
	v_mul_f32_e32 v79, v79, v80
	v_mul_f32_e32 v72, v72, v80
	v_mul_f32_e32 v73, v73, v80
	v_mul_f32_e32 v74, v74, v80
	v_mul_f32_e32 v75, v75, v80
	s_waitcnt vmcnt(0)
; __device__ __forceinline__ unsigned cvt_pk_bf16(float lo, float hi) { unsigned r; asm volatile("v_cvt_pk_bf16_f32 %0, %1, %2" : "=v"(r) : "v"(lo), "v"(hi)); return r; }
; __device__ __forceinline__ float bflo(unsigned w) { return __uint_as_float(w << 16); }
; __device__ __forceinline__ float bfhi(unsigned w) { return __uint_as_float(w & 0xffff0000u); }
; __device__ __forceinline__ float sigm(float x) { return __builtin_amdgcn_rcpf(1.f + __expf(-x)); }
; template <bool STATE_ONLY>
; __device__ __forceinline__ void mlstm_group(const Args& a, LAS unsigned char* lds, int bh, int grp, int tid, int wave, int lane) {
;     ...
;             if (wave == 0) { const float pmx = T_pmx[ci * 64 + lane], bc = T_bc[ci * 64 + lane], mx = fmaxf(m_prev, pmx);
;                 s_rowterm[lane] = -mx; s_dcol[lane] = T_dcol[ci * 64 + lane]; s_iscale[lane] = __expf(m_prev - mx); s_emrow[lane] = __expf(-(bc + mx)); }
;     ...
;             const float* gp = a.gno + h * 128 + seg_n * 16;
;             float ov[16];
; #pragma unroll
;             for (int q = 0; q < 4; ++q) { ov[2 * q] = bflo(og0[q]); ov[2 * q + 1] = bfhi(og0[q]); ov[8 + 2 * q] = bflo(og1[q]); ov[8 + 2 * q + 1] = bfhi(og1[q]); }
;             unsigned pk[8];
; #pragma unroll
;             for (int q = 0; q < 8; ++q) { const float v0 = hv[2 * q] * rn * gp[2 * q] * sigm(ov[2 * q]), v1 = hv[2 * q + 1] * rn * gp[2 * q + 1] * sigm(ov[2 * q + 1]); pk[q] = cvt_pk_bf16(v0, v1); }
;             bf16_t* dst = HO + (rowbase + (size_t)c * 64 + j_n) * DM + h * 128 + seg_n * 16;
;             *(u32x4*)dst = (u32x4){pk[0], pk[1], pk[2], pk[3]}; *(u32x4*)(dst + 8) = (u32x4){pk[4], pk[5], pk[6], pk[7]};
	v_mov_b32_e32 v170, v202
	v_mov_b32_e32 v171, v203
	v_mul_f32_e32 v76, v170, v76
	v_mul_f32_e32 v77, v171, v77
	v_mul_f32_e32 v76, v172, v76
	v_mul_f32_e32 v68, v68, v77
	v_cvt_pk_bf16_f32 v68, v76, v68
	v_lshlrev_b32_e32 v170, 16, v69
	v_and_b32_e32 v69, 0xffff0000, v69
	v_mul_f32_e32 v170, 0xbfb8aa3b, v170
	v_mul_f32_e32 v69, 0xbfb8aa3b, v69
	v_exp_f32_e32 v170, v170
	v_exp_f32_e32 v69, v69
	v_add_f32_e32 v170, 1.0, v170
	v_add_f32_e32 v69, 1.0, v69
	v_rcp_f32_e32 v170, v170
	v_rcp_f32_e32 v69, v69
	v_mov_b32_e32 v76, v204
	v_mov_b32_e32 v77, v205
	v_mul_f32_e32 v76, v76, v78
	v_mul_f32_e32 v77, v77, v79
	v_mul_f32_e32 v76, v170, v76
	v_mul_f32_e32 v69, v69, v77
	v_cvt_pk_bf16_f32 v69, v76, v69
	v_lshlrev_b32_e32 v78, 16, v70
	v_and_b32_e32 v70, 0xffff0000, v70
	v_mul_f32_e32 v78, 0xbfb8aa3b, v78
	v_mul_f32_e32 v70, 0xbfb8aa3b, v70
	v_exp_f32_e32 v78, v78
	v_exp_f32_e32 v70, v70
	v_mul_f32_e32 v79, v162, v80
	v_mul_f32_e32 v162, v163, v80
	v_add_f32_e32 v78, 1.0, v78
	v_add_f32_e32 v70, 1.0, v70
	v_rcp_f32_e32 v78, v78
	v_rcp_f32_e32 v70, v70
	v_mov_b32_e32 v163, s55
	v_mov_b32_e32 v76, v206
	v_mov_b32_e32 v77, v207
	v_mul_f32_e32 v76, v76, v79
	v_mul_f32_e32 v77, v77, v162
	v_mul_f32_e32 v76, v78, v76
	v_mul_f32_e32 v70, v70, v77
	v_cvt_pk_bf16_f32 v70, v76, v70
	v_lshlrev_b32_e32 v78, 16, v71
	v_and_b32_e32 v71, 0xffff0000, v71
	v_mul_f32_e32 v78, 0xbfb8aa3b, v78
	v_mul_f32_e32 v71, 0xbfb8aa3b, v71
	v_exp_f32_e32 v78, v78
	v_exp_f32_e32 v71, v71
	v_mul_f32_e32 v79, v164, v80
	v_mul_f32_e32 v162, v165, v80
	v_add_f32_e32 v78, 1.0, v78
	v_add_f32_e32 v71, 1.0, v71
	v_rcp_f32_e32 v78, v78
	v_rcp_f32_e32 v71, v71
	v_mov_b32_e32 v76, v208
	v_mov_b32_e32 v77, v209
	v_mul_f32_e32 v76, v76, v79
	v_mul_f32_e32 v77, v77, v162
	v_mul_f32_e32 v76, v78, v76
	v_mul_f32_e32 v71, v71, v77
	v_cvt_pk_bf16_f32 v71, v76, v71
	v_lshlrev_b32_e32 v78, 16, v64
	v_and_b32_e32 v64, 0xffff0000, v64
	v_mul_f32_e32 v78, 0xbfb8aa3b, v78
	v_mul_f32_e32 v64, 0xbfb8aa3b, v64
	v_exp_f32_e32 v78, v78
	v_exp_f32_e32 v64, v64
	v_mul_f32_e32 v79, v166, v80
	v_mul_f32_e32 v162, v167, v80
	v_add_f32_e32 v78, 1.0, v78
	v_add_f32_e32 v64, 1.0, v64
	v_rcp_f32_e32 v78, v78
	v_rcp_f32_e32 v64, v64
	v_mov_b32_e32 v76, v210
	v_mov_b32_e32 v77, v211
	v_mul_f32_e32 v76, v76, v79
	v_mul_f32_e32 v77, v162, v77
	v_mul_f32_e32 v76, v78, v76
	v_mul_f32_e32 v64, v64, v77
	v_cvt_pk_bf16_f32 v76, v76, v64
	v_lshlrev_b32_e32 v64, 16, v65
	v_and_b32_e32 v65, 0xffff0000, v65
	v_mul_f32_e32 v64, 0xbfb8aa3b, v64
	v_mul_f32_e32 v65, 0xbfb8aa3b, v65
	v_exp_f32_e32 v64, v64
	v_exp_f32_e32 v65, v65
	v_mul_f32_e32 v77, v168, v80
	v_mul_f32_e32 v162, v169, v80
	v_add_f32_e32 v64, 1.0, v64
	v_add_f32_e32 v65, 1.0, v65
	v_rcp_f32_e32 v64, v64
	v_rcp_f32_e32 v65, v65
	v_mov_b32_e32 v78, v212
	v_mov_b32_e32 v79, v213
	v_mul_f32_e32 v77, v77, v78
	v_mul_f32_e32 v78, v162, v79
	v_mul_f32_e32 v64, v64, v77
	v_mul_f32_e32 v65, v65, v78
	v_cvt_pk_bf16_f32 v77, v64, v65
	v_lshlrev_b32_e32 v78, 16, v66
	v_and_b32_e32 v66, 0xffff0000, v66
	v_mul_f32_e32 v78, 0xbfb8aa3b, v78
	v_mul_f32_e32 v66, 0xbfb8aa3b, v66
	v_exp_f32_e32 v78, v78
	v_exp_f32_e32 v66, v66
	v_mov_b32_e32 v162, s54
	v_add_f32_e32 v78, 1.0, v78
	v_add_f32_e32 v66, 1.0, v66
	v_rcp_f32_e32 v78, v78
	v_rcp_f32_e32 v66, v66
	v_mov_b32_e32 v64, v214
	v_mov_b32_e32 v65, v215
	v_mul_f32_e32 v64, v72, v64
	v_mul_f32_e32 v65, v73, v65
	v_mul_f32_e32 v64, v78, v64
	v_mul_f32_e32 v65, v66, v65
	v_cvt_pk_bf16_f32 v78, v64, v65
	v_lshlrev_b32_e32 v72, 16, v67
	v_and_b32_e32 v73, 0xffff0000, v67
	v_mul_f32_e32 v72, 0xbfb8aa3b, v72
	v_mul_f32_e32 v73, 0xbfb8aa3b, v73
	v_exp_f32_e32 v72, v72
	v_exp_f32_e32 v73, v73
	v_lshl_add_u64 v[66:67], s[74:75], 0, v[98:99]
	v_add_co_u32_e32 v66, vcc, s40, v66
	v_add_f32_e32 v72, 1.0, v72
	v_add_f32_e32 v73, 1.0, v73
	v_rcp_f32_e32 v72, v72
	v_rcp_f32_e32 v73, v73
	v_addc_co_u32_e32 v67, vcc, 0, v67, vcc
	s_and_b64 vcc, exec, s[38:39]
	v_mov_b32_e32 v64, v216
	v_mov_b32_e32 v65, v217
	v_mul_f32_e32 v64, v74, v64
	v_mul_f32_e32 v65, v75, v65
	v_mul_f32_e32 v64, v72, v64
	v_mul_f32_e32 v65, v73, v65
	v_cvt_pk_bf16_f32 v79, v64, v65
	ds_read_b32 v64, v162
	ds_read_b32 v65, v163
	global_store_dwordx4 v[66:67], v[68:71], off
	global_store_dwordx4 v[66:67], v[76:79], off offset:16
	s_cbranch_vccnz .LBB0_1249
	v_add_u32_e32 v66, 0x1bb00, v156
	ds_read_b32 v66, v66
	v_add_u32_e32 v67, 0x1c300, v156
	v_add_u32_e32 v68, 0x1b300, v156
	ds_read_b32 v67, v67
	ds_read_b32 v68, v68
	v_max_f32_e64 v69, -v154, -v154
	s_waitcnt lgkmcnt(2)
	v_max_f32_e64 v66, -v66, -v66
	v_min_f32_e32 v66, v69, v66
	v_add_f32_e32 v69, v154, v66
	v_mul_f32_e32 v69, 0x3fb8aa3b, v69
	s_waitcnt lgkmcnt(1)
	v_sub_f32_e32 v67, v67, v66
	v_exp_f32_e32 v69, v69
	v_mul_f32_e32 v67, 0xbfb8aa3b, v67
	v_exp_f32_e32 v67, v67
	ds_write_b32 v120, v66
	s_waitcnt lgkmcnt(1)
	ds_write_b32 v121, v68
	ds_write_b32 v122, v69
	ds_write_b32 v123, v67
